# topk scoring: weighted sum by v_pk_fma_f32 pairs (8 packed instead of 16 scalar FMAs per query), MFMA every 6 VALU
# baseline (speedup 1.0000x reference)
.LBB0_703:
	s_mov_b32 s94, 0x7fff0000
	s_mov_b32 s95, 0x7fff0000
	s_mov_b32 s97, 0
	v_lshlrev_b32_e32 v238, 2, v121
	v_mov_b32_e32 v244, v91
	v_mov_b32_e32 v245, v93
	v_mov_b32_e32 v246, v95
	v_mov_b32_e32 v247, v129
	v_readfirstlane_b32 s16, v0
	s_nop 3
	s_lshr_b32 s16, s16, 6
	s_cmp_ge_u32 s16, 4
	s_cbranch_scc0 .Ltk_noprio
	s_setprio 1

.Ltk_e_go:
	v_med3_f32 v194, v194, 0, v125
	v_mfma_f32_32x32x16_bf16 v[2:17], v[58:61], v[162:165], 0
	v_med3_f32 v195, v195, 0, v125
	v_pk_mul_f32 v[226:227], v[244:245], v[194:195]
	v_med3_f32 v196, v196, 0, v125
	v_med3_f32 v197, v197, 0, v125
	v_pk_fma_f32 v[226:227], v[246:247], v[196:197], v[226:227]
	v_med3_f32 v198, v198, 0, v125
	v_mfma_f32_32x32x16_bf16 v[18:33], v[74:77], v[162:165], 0
	v_med3_f32 v199, v199, 0, v125
	v_pk_fma_f32 v[226:227], v[130:131], v[198:199], v[226:227]
	v_med3_f32 v200, v200, 0, v125
	v_med3_f32 v201, v201, 0, v125
	v_pk_fma_f32 v[226:227], v[132:133], v[200:201], v[226:227]
	v_med3_f32 v202, v202, 0, v125
	v_mfma_f32_32x32x16_bf16 v[2:17], v[50:53], v[166:169], v[2:17]
	v_med3_f32 v203, v203, 0, v125
	v_pk_fma_f32 v[226:227], v[134:135], v[202:203], v[226:227]
	v_med3_f32 v204, v204, 0, v125
	v_med3_f32 v205, v205, 0, v125
	v_pk_fma_f32 v[226:227], v[136:137], v[204:205], v[226:227]
	v_med3_f32 v206, v206, 0, v125
	v_mfma_f32_32x32x16_bf16 v[18:33], v[66:69], v[166:169], v[18:33]
	v_med3_f32 v207, v207, 0, v125
	v_pk_fma_f32 v[226:227], v[138:139], v[206:207], v[226:227]
	v_med3_f32 v208, v208, 0, v125
	v_med3_f32 v209, v209, 0, v125
	v_pk_fma_f32 v[226:227], v[140:141], v[208:209], v[226:227]
	v_add_f32_e32 v230, v227, v226
	v_mfma_f32_32x32x16_bf16 v[2:17], v[54:57], v[170:173], v[2:17]
	v_med3_f32 v210, v210, 0, v125
	v_med3_f32 v211, v211, 0, v125
	v_pk_mul_f32 v[228:229], v[142:143], v[210:211]
	v_med3_f32 v212, v212, 0, v125
	v_med3_f32 v213, v213, 0, v125
	v_pk_fma_f32 v[228:229], v[144:145], v[212:213], v[228:229]
	v_mfma_f32_32x32x16_bf16 v[18:33], v[70:73], v[170:173], v[18:33]
	v_med3_f32 v214, v214, 0, v125
	v_med3_f32 v215, v215, 0, v125
	v_pk_fma_f32 v[228:229], v[146:147], v[214:215], v[228:229]
	v_med3_f32 v216, v216, 0, v125
	v_med3_f32 v217, v217, 0, v125
	v_pk_fma_f32 v[228:229], v[148:149], v[216:217], v[228:229]
	v_mfma_f32_32x32x16_bf16 v[2:17], v[62:65], v[174:177], v[2:17]
	v_med3_f32 v218, v218, 0, v125
	v_med3_f32 v219, v219, 0, v125
	v_pk_fma_f32 v[228:229], v[150:151], v[218:219], v[228:229]
	v_med3_f32 v220, v220, 0, v125
	v_med3_f32 v221, v221, 0, v125
	v_pk_fma_f32 v[228:229], v[152:153], v[220:221], v[228:229]
	v_mfma_f32_32x32x16_bf16 v[18:33], v[78:81], v[174:177], v[18:33]
	v_med3_f32 v222, v222, 0, v125
	v_med3_f32 v223, v223, 0, v125
	v_pk_fma_f32 v[228:229], v[154:155], v[222:223], v[228:229]
	v_med3_f32 v224, v224, 0, v125
	v_med3_f32 v225, v225, 0, v125
	v_pk_fma_f32 v[228:229], v[156:157], v[224:225], v[228:229]
	v_add_f32_e32 v231, v229, v228
	s_lshl_b32 s16, s95, 2
	s_add_u32 s68, s36, s16
	s_addc_u32 s69, s37, 0
	s_sub_i32 s96, s22, s95
	v_permlane32_swap_b32_e32 v230, v231
	v_add_f32_e32 v232, v230, v231
	v_cmp_gt_i32_e32 vcc, s96, v100
	s_and_saveexec_b64 s[18:19], vcc
	global_store_dword v238, v232, s[68:69]
	v_ashrrev_i32_e32 v233, 31, v232
	v_or_b32_e32 v233, 0x80000000, v233
	v_xor_b32_e32 v233, v232, v233
	v_bfe_u32 v233, v233, 22, 10
	v_lshl_add_u32 v233, v233, 2, v119
	ds_add_u32 v233, v124
	s_or_b64 exec, exec, s[18:19]
	s_mov_b32 s94, s33
	s_add_i32 s16, s33, 32
	s_cmp_gt_i32 s16, s23
	s_cbranch_scc1 .Ltk_drain_e
	s_add_i32 s17, s33, 64
	s_cmpk_eq_i32 s31, 0xc0
	s_cbranch_scc1 .Ltk_o_nob0
	s_cmp_gt_i32 s17, s23
	s_cbranch_scc1 .Ltk_o_nob0
	ds_read_b128 v[162:165], v160 offset:9216
	ds_read_b128 v[166:169], v160 offset:9248
	ds_read_b128 v[170:173], v160 offset:9280
	ds_read_b128 v[174:177], v160 offset:9312
	s_waitcnt lgkmcnt(4)
	s_branch .Ltk_o_go

.Ltk_o_go:
	v_med3_f32 v2, v2, 0, v125
	v_mfma_f32_32x32x16_bf16 v[194:209], v[58:61], v[178:181], 0
	v_med3_f32 v3, v3, 0, v125
	v_pk_mul_f32 v[226:227], v[244:245], v[2:3]
	v_med3_f32 v4, v4, 0, v125
	v_med3_f32 v5, v5, 0, v125
	v_pk_fma_f32 v[226:227], v[246:247], v[4:5], v[226:227]
	v_med3_f32 v6, v6, 0, v125
	v_mfma_f32_32x32x16_bf16 v[210:225], v[74:77], v[178:181], 0
	v_med3_f32 v7, v7, 0, v125
	v_pk_fma_f32 v[226:227], v[130:131], v[6:7], v[226:227]
	v_med3_f32 v8, v8, 0, v125
	v_med3_f32 v9, v9, 0, v125
	v_pk_fma_f32 v[226:227], v[132:133], v[8:9], v[226:227]
	v_med3_f32 v10, v10, 0, v125
	v_mfma_f32_32x32x16_bf16 v[194:209], v[50:53], v[182:185], v[194:209]
	v_med3_f32 v11, v11, 0, v125
	v_pk_fma_f32 v[226:227], v[134:135], v[10:11], v[226:227]
	v_med3_f32 v12, v12, 0, v125
	v_med3_f32 v13, v13, 0, v125
	v_pk_fma_f32 v[226:227], v[136:137], v[12:13], v[226:227]
	v_med3_f32 v14, v14, 0, v125
	v_mfma_f32_32x32x16_bf16 v[210:225], v[66:69], v[182:185], v[210:225]
	v_med3_f32 v15, v15, 0, v125
	v_pk_fma_f32 v[226:227], v[138:139], v[14:15], v[226:227]
	v_med3_f32 v16, v16, 0, v125
	v_med3_f32 v17, v17, 0, v125
	v_pk_fma_f32 v[226:227], v[140:141], v[16:17], v[226:227]
	v_add_f32_e32 v230, v227, v226
	v_mfma_f32_32x32x16_bf16 v[194:209], v[54:57], v[186:189], v[194:209]
	v_med3_f32 v18, v18, 0, v125
	v_med3_f32 v19, v19, 0, v125
	v_pk_mul_f32 v[228:229], v[142:143], v[18:19]
	v_med3_f32 v20, v20, 0, v125
	v_med3_f32 v21, v21, 0, v125
	v_pk_fma_f32 v[228:229], v[144:145], v[20:21], v[228:229]
	v_mfma_f32_32x32x16_bf16 v[210:225], v[70:73], v[186:189], v[210:225]
	v_med3_f32 v22, v22, 0, v125
	v_med3_f32 v23, v23, 0, v125
	v_pk_fma_f32 v[228:229], v[146:147], v[22:23], v[228:229]
	v_med3_f32 v24, v24, 0, v125
	v_med3_f32 v25, v25, 0, v125
	v_pk_fma_f32 v[228:229], v[148:149], v[24:25], v[228:229]
	v_mfma_f32_32x32x16_bf16 v[194:209], v[62:65], v[190:193], v[194:209]
	v_med3_f32 v26, v26, 0, v125
	v_med3_f32 v27, v27, 0, v125
	v_pk_fma_f32 v[228:229], v[150:151], v[26:27], v[228:229]
	v_med3_f32 v28, v28, 0, v125
	v_med3_f32 v29, v29, 0, v125
	v_pk_fma_f32 v[228:229], v[152:153], v[28:29], v[228:229]
	v_mfma_f32_32x32x16_bf16 v[210:225], v[78:81], v[190:193], v[210:225]
	v_med3_f32 v30, v30, 0, v125
	v_med3_f32 v31, v31, 0, v125
	v_pk_fma_f32 v[228:229], v[154:155], v[30:31], v[228:229]
	v_med3_f32 v32, v32, 0, v125
	v_med3_f32 v33, v33, 0, v125
	v_pk_fma_f32 v[228:229], v[156:157], v[32:33], v[228:229]
	v_add_f32_e32 v231, v229, v228
	s_lshl_b32 s16, s94, 2
	s_add_u32 s68, s36, s16
	s_addc_u32 s69, s37, 0
	s_sub_i32 s96, s22, s94
	v_permlane32_swap_b32_e32 v230, v231
	v_add_f32_e32 v232, v230, v231
	v_cmp_gt_i32_e32 vcc, s96, v100
	s_and_saveexec_b64 s[18:19], vcc
	global_store_dword v238, v232, s[68:69]
	v_ashrrev_i32_e32 v233, 31, v232
	v_or_b32_e32 v233, 0x80000000, v233
	v_xor_b32_e32 v233, v232, v233
	v_bfe_u32 v233, v233, 22, 10
	v_lshl_add_u32 v233, v233, 2, v119
	ds_add_u32 v233, v124
	s_or_b64 exec, exec, s[18:19]
	s_add_i32 s95, s33, 32
	s_add_i32 s17, s33, 64
	s_cmp_gt_i32 s17, s23
	s_cbranch_scc1 .Ltk_drain_o
	s_cmpk_eq_i32 s31, 0xc0
	s_cbranch_scc1 .Ltk_blockend
	s_add_i32 s31, s31, 64
	v_add_u32_e32 v160, 0x2400, v160
	s_branch .Ltk_pair

.Ltk_drain_e:
	v_med3_f32 v2, v2, 0, v125
	v_med3_f32 v3, v3, 0, v125
	v_pk_mul_f32 v[226:227], v[244:245], v[2:3]
	v_med3_f32 v4, v4, 0, v125
	v_med3_f32 v5, v5, 0, v125
	v_pk_fma_f32 v[226:227], v[246:247], v[4:5], v[226:227]
	v_med3_f32 v6, v6, 0, v125
	v_med3_f32 v7, v7, 0, v125
	v_pk_fma_f32 v[226:227], v[130:131], v[6:7], v[226:227]
	v_med3_f32 v8, v8, 0, v125
	v_med3_f32 v9, v9, 0, v125
	v_pk_fma_f32 v[226:227], v[132:133], v[8:9], v[226:227]
	v_med3_f32 v10, v10, 0, v125
	v_med3_f32 v11, v11, 0, v125
	v_pk_fma_f32 v[226:227], v[134:135], v[10:11], v[226:227]
	v_med3_f32 v12, v12, 0, v125
	v_med3_f32 v13, v13, 0, v125
	v_pk_fma_f32 v[226:227], v[136:137], v[12:13], v[226:227]
	v_med3_f32 v14, v14, 0, v125
	v_med3_f32 v15, v15, 0, v125
	v_pk_fma_f32 v[226:227], v[138:139], v[14:15], v[226:227]
	v_med3_f32 v16, v16, 0, v125
	v_med3_f32 v17, v17, 0, v125
	v_pk_fma_f32 v[226:227], v[140:141], v[16:17], v[226:227]
	v_add_f32_e32 v230, v227, v226
	v_med3_f32 v18, v18, 0, v125
	v_med3_f32 v19, v19, 0, v125
	v_pk_mul_f32 v[228:229], v[142:143], v[18:19]
	v_med3_f32 v20, v20, 0, v125
	v_med3_f32 v21, v21, 0, v125
	v_pk_fma_f32 v[228:229], v[144:145], v[20:21], v[228:229]
	v_med3_f32 v22, v22, 0, v125
	v_med3_f32 v23, v23, 0, v125
	v_pk_fma_f32 v[228:229], v[146:147], v[22:23], v[228:229]
	v_med3_f32 v24, v24, 0, v125
	v_med3_f32 v25, v25, 0, v125
	v_pk_fma_f32 v[228:229], v[148:149], v[24:25], v[228:229]
	v_med3_f32 v26, v26, 0, v125
	v_med3_f32 v27, v27, 0, v125
	v_pk_fma_f32 v[228:229], v[150:151], v[26:27], v[228:229]
	v_med3_f32 v28, v28, 0, v125
	v_med3_f32 v29, v29, 0, v125
	v_pk_fma_f32 v[228:229], v[152:153], v[28:29], v[228:229]
	v_med3_f32 v30, v30, 0, v125
	v_med3_f32 v31, v31, 0, v125
	v_pk_fma_f32 v[228:229], v[154:155], v[30:31], v[228:229]
	v_med3_f32 v32, v32, 0, v125
	v_med3_f32 v33, v33, 0, v125
	v_pk_fma_f32 v[228:229], v[156:157], v[32:33], v[228:229]
	v_add_f32_e32 v231, v229, v228
	s_lshl_b32 s16, s94, 2
	s_add_u32 s68, s36, s16
	s_addc_u32 s69, s37, 0
	s_sub_i32 s96, s22, s94
	v_permlane32_swap_b32_e32 v230, v231
	v_add_f32_e32 v232, v230, v231
	v_cmp_gt_i32_e32 vcc, s96, v100
	s_and_saveexec_b64 s[18:19], vcc
	global_store_dword v238, v232, s[68:69]
	v_ashrrev_i32_e32 v233, 31, v232
	v_or_b32_e32 v233, 0x80000000, v233
	v_xor_b32_e32 v233, v232, v233
	v_bfe_u32 v233, v233, 22, 10
	v_lshl_add_u32 v233, v233, 2, v119
	ds_add_u32 v233, v124
	s_or_b64 exec, exec, s[18:19]
	s_branch .Ltk_done
.Ltk_drain_o:
	v_med3_f32 v194, v194, 0, v125
	v_med3_f32 v195, v195, 0, v125
	v_pk_mul_f32 v[226:227], v[244:245], v[194:195]
	v_med3_f32 v196, v196, 0, v125
	v_med3_f32 v197, v197, 0, v125
	v_pk_fma_f32 v[226:227], v[246:247], v[196:197], v[226:227]
	v_med3_f32 v198, v198, 0, v125
	v_med3_f32 v199, v199, 0, v125
	v_pk_fma_f32 v[226:227], v[130:131], v[198:199], v[226:227]
	v_med3_f32 v200, v200, 0, v125
	v_med3_f32 v201, v201, 0, v125
	v_pk_fma_f32 v[226:227], v[132:133], v[200:201], v[226:227]
	v_med3_f32 v202, v202, 0, v125
	v_med3_f32 v203, v203, 0, v125
	v_pk_fma_f32 v[226:227], v[134:135], v[202:203], v[226:227]
	v_med3_f32 v204, v204, 0, v125
	v_med3_f32 v205, v205, 0, v125
	v_pk_fma_f32 v[226:227], v[136:137], v[204:205], v[226:227]
	v_med3_f32 v206, v206, 0, v125
	v_med3_f32 v207, v207, 0, v125
	v_pk_fma_f32 v[226:227], v[138:139], v[206:207], v[226:227]
	v_med3_f32 v208, v208, 0, v125
	v_med3_f32 v209, v209, 0, v125
	v_pk_fma_f32 v[226:227], v[140:141], v[208:209], v[226:227]
	v_add_f32_e32 v230, v227, v226
	v_med3_f32 v210, v210, 0, v125
	v_med3_f32 v211, v211, 0, v125
	v_pk_mul_f32 v[228:229], v[142:143], v[210:211]
	v_med3_f32 v212, v212, 0, v125
	v_med3_f32 v213, v213, 0, v125
	v_pk_fma_f32 v[228:229], v[144:145], v[212:213], v[228:229]
	v_med3_f32 v214, v214, 0, v125
	v_med3_f32 v215, v215, 0, v125
	v_pk_fma_f32 v[228:229], v[146:147], v[214:215], v[228:229]
	v_med3_f32 v216, v216, 0, v125
	v_med3_f32 v217, v217, 0, v125
	v_pk_fma_f32 v[228:229], v[148:149], v[216:217], v[228:229]
	v_med3_f32 v218, v218, 0, v125
	v_med3_f32 v219, v219, 0, v125
	v_pk_fma_f32 v[228:229], v[150:151], v[218:219], v[228:229]
	v_med3_f32 v220, v220, 0, v125
	v_med3_f32 v221, v221, 0, v125
	v_pk_fma_f32 v[228:229], v[152:153], v[220:221], v[228:229]
	v_med3_f32 v222, v222, 0, v125
	v_med3_f32 v223, v223, 0, v125
	v_pk_fma_f32 v[228:229], v[154:155], v[222:223], v[228:229]
	v_med3_f32 v224, v224, 0, v125
	v_med3_f32 v225, v225, 0, v125
	v_pk_fma_f32 v[228:229], v[156:157], v[224:225], v[228:229]
	v_add_f32_e32 v231, v229, v228
	s_lshl_b32 s16, s95, 2
	s_add_u32 s68, s36, s16
	s_addc_u32 s69, s37, 0
	s_sub_i32 s96, s22, s95
	v_permlane32_swap_b32_e32 v230, v231
	v_add_f32_e32 v232, v230, v231
	v_cmp_gt_i32_e32 vcc, s96, v100
	s_and_saveexec_b64 s[18:19], vcc
	global_store_dword v238, v232, s[68:69]
	v_ashrrev_i32_e32 v233, 31, v232
	v_or_b32_e32 v233, 0x80000000, v233
	v_xor_b32_e32 v233, v232, v233
	v_bfe_u32 v233, v233, 22, 10
	v_lshl_add_u32 v233, v233, 2, v119
	ds_add_u32 v233, v124
	s_or_b64 exec, exec, s[18:19]
